# scan: third register set, global loads issued 4 chunks ahead of use (staging still 2 ahead)
# speedup vs baseline: 1.0089x; 1.0072x over previous
; #define SCAN_BAR() asm volatile("s_waitcnt lgkmcnt(0)\n\ts_barrier" ::: "memory")
; __device__ void scan_phase(LAS unsigned char* lds, const Params& p) {
;     ...
;     for (int item = blockIdx.x; item < 256; item += gridDim.x) {
;         const int seq = (item & 7) + 8 * (item >> 5), es = (item >> 3) & 3;
;         const int dir = seq & 1, h = (seq >> 1) & 3, b = seq >> 3;
;         const char* Qx = (const char*)((const bf16_t*)(p.ws + (dir ? WS_QB : WS_QF)) + h * 128);
;         const char* Kx = (const char*)((const bf16_t*)(p.ws + (dir ? WS_KB : WS_KF)) + h * 128);
;         const char* Vx = (const char*)((const bf16_t*)(p.ws + WS_V) + h * 128 + es * 32);
;         const char* Rx = (const char*)(RT + (size_t)dir * NCHUNK * 512 + h * 128);
;         const char* Tx = (const char*)(RT + (size_t)(2 + dir) * NCHUNK * 512 + h * 128);
;         const unsigned qoff0 = (unsigned)((dir ? 63 - (tid >> 4) : (tid >> 4)) * 1024 + (tid & 15) * 16), qstep = dir ? (unsigned)-32768 : 32768u;
;         const unsigned voff = (unsigned)((dir ? 63 - (tid >> 3) : (tid >> 3)) * 1024 + (tid & 7) * 8), roff = (unsigned)(tid & 127) * 4u;
;         f32x4 S[2] = {(f32x4){0.f, 0.f, 0.f, 0.f}, (f32x4){0.f, 0.f, 0.f, 0.f}};
;         float tailp = 0.f;
;         u32x4 k4A[2], k4B[2], k4C[2], k4D[2]; u32x4 q4A[2], q4B[2], q4C[2], q4D[2]; u32x2 v4A, v4B, v4C, v4D; float rvA, tlA, rvB, tlB, rvC, tlC, rvD, tlD;
;     ...
;         SCAN_LOAD(0, k4A, q4A, v4A, rvA, tlA); SCAN_LOAD(1, k4B, q4B, v4B, rvB, tlB); SCAN_LOAD(2, k4C, q4C, v4C, rvC, tlC); SCAN_LOAD(3, k4D, q4D, v4D, rvD, tlD);
;         SCAN_STAGE(0, k4A, q4A, v4A, rvA, tlA); SCAN_LOAD(4, k4A, q4A, v4A, rvA, tlA);
;         SCAN_BAR();
.Lsc3_item:
	s_and_b32 s10, s9, 1
	s_lshr_b32 s3, s9, 1
	s_and_b32 s3, s3, 3
	s_lshr_b32 s4, s9, 5
	s_lshr_b32 s5, s9, 3
	s_and_b32 s5, s5, 3
	s_cmp_eq_u32 s10, 0
	s_cselect_b32 s15, 1, -1
	s_cselect_b32 s64, 0, 3
	s_cselect_b32 s65, -4, 0x43
	s_lshl_b32 s16, s4, 2
	s_add_u32 s16, s16, 0x200
	s_lshl_b32 s17, s4, 6
	s_add_u32 s16, s16, s64
	s_add_i32 s17, s17, s65
	s_lshl_b32 s3, s3, 8
	s_lshl_b32 s5, s5, 6
	s_cmp_eq_u32 s10, 0
	s_mov_b32 s65, 0x5100000
	s_cselect_b32 s64, s65, 0x7300000
	s_add_u32 s64, s64, s3
	s_add_u32 s18, s70, s64
	s_addc_u32 s19, s71, 0
	s_cmp_eq_u32 s10, 0
	s_mov_b32 s65, 0x9500000
	s_cselect_b32 s64, s65, 0xb700000
	s_add_u32 s64, s64, s3
	s_add_u32 s20, s70, s64
	s_addc_u32 s21, s71, 0
	s_add_u32 s64, s3, s5
	s_add_u32 s65, s64, 0xd900000
	s_add_u32 s22, s70, s65
	s_addc_u32 s23, s71, 0
	s_lshl_b32 s65, s10, 25
	s_add_u32 s64, s64, s65
	s_add_u32 s28, s68, s64
	s_addc_u32 s29, s69, 0
	s_mul_i32 s64, s10, 0x110000
	s_lshl_b32 s65, s3, 1
	s_add_u32 s64, s64, s65
	s_add_u32 s64, s64, 0x15b00000
	s_add_u32 s24, s70, s64
	s_addc_u32 s25, s71, 0
	s_add_u32 s26, s24, 0x220000
	s_addc_u32 s27, s25, 0
	s_lshl_b32 s64, s9, 16
	s_add_u32 s64, s64, 0xd00000
	s_add_u32 s30, s70, s64
	s_addc_u32 s31, s71, 0
	s_mul_i32 s5, s10, 63
	s_lshl_b32 s3, s7, 4
	v_add_u32_e32 v1, s3, v58
	v_xor_b32_e32 v1, s5, v1
	v_lshlrev_b32_e32 v1, 10, v1
	s_lshl_b32 s3, s8, 5
	v_lshl_add_u32 v57, v59, 3, v1
	v_add_u32_e32 v57, s3, v57
	v_lshrrev_b32_e32 v1, 4, v0
	v_xor_b32_e32 v93, s5, v1
	v_lshlrev_b32_e32 v93, 10, v93
	v_lshl_add_u32 v53, v58, 4, v93
	v_add_u32_e32 v1, 32, v1
	v_xor_b32_e32 v93, s5, v1
	v_lshlrev_b32_e32 v93, 10, v93
	v_lshl_add_u32 v54, v58, 4, v93
	v_lshrrev_b32_e32 v1, 3, v0
	v_xor_b32_e32 v1, s5, v1
	v_lshlrev_b32_e32 v1, 10, v1
	v_and_b32_e32 v93, 7, v0
	v_lshl_add_u32 v55, v93, 3, v1
	v_mov_b32_e32 v42, 0
	v_mov_b32_e32 v43, 0
	v_mov_b32_e32 v44, 0
	v_mov_b32_e32 v45, 0
	v_mov_b32_e32 v46, 0
	v_mov_b32_e32 v47, 0
	v_mov_b32_e32 v48, 0
	v_mov_b32_e32 v49, 0
	v_mov_b32_e32 v52, 0
	v_mov_b32_e32 v160, 0
	v_mov_b32_e32 v161, 0
	v_mov_b32_e32 v162, 0
	v_mov_b32_e32 v163, 0
	v_mov_b32_e32 v176, 0
	v_mov_b32_e32 v177, 0
	s_mov_b32 s3, 0
	s_cmp_lt_u32 s3, 4
	s_cselect_b32 s4, s16, s17
	s_mul_i32 s5, s3, s15
	s_add_i32 s4, s4, s5
	s_lshl_b32 s5, s4, 16
	s_lshl_b32 s4, s4, 11
	s_add_u32 s40, s18, s5
	s_addc_u32 s41, s19, 0
	s_add_u32 s42, s20, s5
	s_addc_u32 s43, s21, 0
	s_add_u32 s44, s22, s5
	s_addc_u32 s45, s23, 0
	s_add_u32 s46, s24, s4
	s_addc_u32 s47, s25, 0
	s_add_u32 s50, s26, s4
	s_addc_u32 s51, s27, 0
	global_load_dwordx4 v[2:5], v53, s[40:41]
	global_load_dwordx4 v[6:9], v54, s[40:41]
	global_load_dwordx4 v[10:13], v53, s[42:43]
	global_load_dwordx4 v[14:17], v54, s[42:43]
	global_load_dwordx2 v[18:19], v55, s[44:45]
	global_load_dword v20, v56, s[46:47]
	global_load_dword v21, v56, s[50:51]
	s_mov_b32 s3, 1
	s_cmp_lt_u32 s3, 4
	s_cselect_b32 s4, s16, s17
	s_mul_i32 s5, s3, s15
	s_add_i32 s4, s4, s5
	s_lshl_b32 s5, s4, 16
	s_lshl_b32 s4, s4, 11
	s_add_u32 s40, s18, s5
	s_addc_u32 s41, s19, 0
	s_add_u32 s42, s20, s5
	s_addc_u32 s43, s21, 0
	s_add_u32 s44, s22, s5
	s_addc_u32 s45, s23, 0
	s_add_u32 s46, s24, s4
	s_addc_u32 s47, s25, 0
	s_add_u32 s50, s26, s4
	s_addc_u32 s51, s27, 0
	global_load_dwordx4 v[22:25], v53, s[40:41]
	global_load_dwordx4 v[26:29], v54, s[40:41]
	global_load_dwordx4 v[30:33], v53, s[42:43]
	global_load_dwordx4 v[34:37], v54, s[42:43]
	global_load_dwordx2 v[38:39], v55, s[44:45]
	global_load_dword v40, v56, s[46:47]
	global_load_dword v41, v56, s[50:51]
	s_waitcnt vmcnt(0)
	ds_write_b128 v60, v[2:5] offset:0
	ds_write_b128 v60, v[6:9] offset:8704
	ds_write_b128 v60, v[10:13] offset:17408
	ds_write_b128 v60, v[14:17] offset:26112
	ds_write_b64 v63, v[18:19] offset:34816
	v_add_f32_e32 v92, v20, v52
	v_mul_f32_e32 v92, 0x3fb8aa3b, v92
	v_exp_f32_e32 v92, v92
	v_mov_b32_e32 v52, v21
	ds_write_b32 v78, v92 offset:0
	ds_write_b128 v61, v[22:25] offset:0
	ds_write_b128 v61, v[26:29] offset:8704
	ds_write_b128 v61, v[30:33] offset:17408
	ds_write_b128 v61, v[34:37] offset:26112
	ds_write_b64 v64, v[38:39] offset:34816
	v_add_f32_e32 v92, v40, v52
	v_mul_f32_e32 v92, 0x3fb8aa3b, v92
	v_exp_f32_e32 v92, v92
	v_mov_b32_e32 v52, v41
	ds_write_b32 v78, v92 offset:512
	s_mov_b32 s3, 2
	s_cmp_lt_u32 s3, 4
	s_cselect_b32 s4, s16, s17
	s_mul_i32 s5, s3, s15
	s_add_i32 s4, s4, s5
	s_lshl_b32 s5, s4, 16
	s_lshl_b32 s4, s4, 11
	s_add_u32 s40, s18, s5
	s_addc_u32 s41, s19, 0
	s_add_u32 s42, s20, s5
	s_addc_u32 s43, s21, 0
	s_add_u32 s44, s22, s5
	s_addc_u32 s45, s23, 0
	s_add_u32 s46, s24, s4
	s_addc_u32 s47, s25, 0
	s_add_u32 s50, s26, s4
	s_addc_u32 s51, s27, 0
	global_load_dwordx4 v[180:183], v53, s[40:41]
	global_load_dwordx4 v[184:187], v54, s[40:41]
	global_load_dwordx4 v[188:191], v53, s[42:43]
	global_load_dwordx4 v[192:195], v54, s[42:43]
	global_load_dwordx2 v[196:197], v55, s[44:45]
	global_load_dword v198, v56, s[46:47]
	global_load_dword v199, v56, s[50:51]
	global_store_dwordx2 v57, v[176:177], s[30:31]
	s_mov_b32 s3, 3
	s_cmp_lt_u32 s3, 4
	s_cselect_b32 s4, s16, s17
	s_mul_i32 s5, s3, s15
	s_add_i32 s4, s4, s5
	s_lshl_b32 s5, s4, 16
	s_lshl_b32 s4, s4, 11
	s_add_u32 s40, s18, s5
	s_addc_u32 s41, s19, 0
	s_add_u32 s42, s20, s5
	s_addc_u32 s43, s21, 0
	s_add_u32 s44, s22, s5
	s_addc_u32 s45, s23, 0
	s_add_u32 s46, s24, s4
	s_addc_u32 s47, s25, 0
	s_add_u32 s50, s26, s4
	s_addc_u32 s51, s27, 0
	global_load_dwordx4 v[2:5], v53, s[40:41]
	global_load_dwordx4 v[6:9], v54, s[40:41]
	global_load_dwordx4 v[10:13], v53, s[42:43]
	global_load_dwordx4 v[14:17], v54, s[42:43]
	global_load_dwordx2 v[18:19], v55, s[44:45]
	global_load_dword v20, v56, s[46:47]
	global_load_dword v21, v56, s[50:51]
	global_store_dwordx2 v57, v[176:177], s[30:31]
	s_waitcnt lgkmcnt(0)
	s_barrier
	s_mov_b32 s34, 0

.Lsc3_noy_0:
	s_add_u32 s3, s34, 4
	s_min_u32 s3, s3, 67
	s_cmp_lt_u32 s3, 4
	s_cselect_b32 s4, s16, s17
	s_mul_i32 s5, s3, s15
	s_add_i32 s4, s4, s5
	s_lshl_b32 s5, s4, 16
	s_lshl_b32 s4, s4, 11
	s_add_u32 s40, s18, s5
	s_addc_u32 s41, s19, 0
	s_add_u32 s42, s20, s5
	s_addc_u32 s43, s21, 0
	s_add_u32 s44, s22, s5
	s_addc_u32 s45, s23, 0
	s_add_u32 s46, s24, s4
	s_addc_u32 s47, s25, 0
	s_add_u32 s50, s26, s4
	s_addc_u32 s51, s27, 0
	global_load_dwordx4 v[22:25], v53, s[40:41]
	global_load_dwordx4 v[26:29], v54, s[40:41]
	global_load_dwordx4 v[30:33], v53, s[42:43]
	global_load_dwordx4 v[34:37], v54, s[42:43]
	global_load_dwordx2 v[38:39], v55, s[44:45]
	global_load_dword v40, v56, s[46:47]
	global_load_dword v41, v56, s[50:51]
	s_waitcnt lgkmcnt(0)
	s_cmp_eq_u32 s13, 0
	s_cbranch_scc1 .Lsc3_nox2_0
	v_mfma_f32_16x16x32_bf16 v[152:155], v[112:115], v[96:99], 0
	v_mfma_f32_16x16x32_bf16 v[152:155], v[116:119], v[100:103], v[152:155]
	v_mfma_f32_16x16x32_bf16 v[152:155], v[120:123], v[104:107], v[152:155]
	v_mfma_f32_16x16x32_bf16 v[152:155], v[124:127], v[108:111], v[152:155]

.Lsc3_noy3_0:
	ds_write_b64 v84, v[160:161]
	ds_write_b64 v84, v[162:163] offset:1024
	s_waitcnt lgkmcnt(0)
	s_barrier
	ds_read_b64_tr_b16 v[112:113], v82 offset:0
	ds_read_b64_tr_b16 v[114:115], v82 offset:288
	ds_read_b64_tr_b16 v[116:117], v82 offset:2304
	ds_read_b64_tr_b16 v[118:119], v82 offset:2592
	ds_read_b64_tr_b16 v[120:121], v82 offset:4608
	ds_read_b64_tr_b16 v[122:123], v82 offset:4896
	ds_read_b64_tr_b16 v[124:125], v82 offset:6912
	ds_read_b64_tr_b16 v[126:127], v82 offset:7200
	ds_read_b64_tr_b16 v[128:129], v72 offset:34816
	ds_read_b64_tr_b16 v[130:131], v72 offset:35968
	ds_read_b64_tr_b16 v[132:133], v72 offset:37120
	ds_read_b64_tr_b16 v[134:135], v72 offset:38272
	ds_read_b128 v[164:167], v86
	ds_read_b128 v[168:171], v86 offset:1024
	s_waitcnt lgkmcnt(12)
	v_mfma_f32_16x16x32_bf16 v[172:175], v[112:115], v[96:99], 0
	ds_read_b64_tr_b16 v[136:137], v75 offset:17408
	ds_read_b64_tr_b16 v[138:139], v75 offset:21760
	s_waitcnt lgkmcnt(12)
	v_mfma_f32_16x16x32_bf16 v[172:175], v[116:119], v[100:103], v[172:175]
	ds_read_b64_tr_b16 v[140:141], v75 offset:17440
	ds_read_b64_tr_b16 v[142:143], v75 offset:21792
	s_waitcnt lgkmcnt(12)
	v_mfma_f32_16x16x32_bf16 v[172:175], v[120:123], v[104:107], v[172:175]
	ds_read_b64_tr_b16 v[144:145], v75 offset:26112
	ds_read_b64_tr_b16 v[146:147], v75 offset:30464
	s_waitcnt lgkmcnt(12)
	v_mfma_f32_16x16x32_bf16 v[172:175], v[124:127], v[108:111], v[172:175]
	ds_read_b64_tr_b16 v[148:149], v75 offset:26144
	ds_read_b64_tr_b16 v[150:151], v75 offset:30496
	s_waitcnt lgkmcnt(9)
	v_mfma_f32_16x16x32_bf16 v[172:175], v[128:131], v[164:167], v[172:175]
	s_waitcnt vmcnt(16)
	ds_write_b128 v62, v[180:183] offset:0
	ds_write_b128 v62, v[184:187] offset:8704
	ds_write_b128 v62, v[188:191] offset:17408
	ds_write_b128 v62, v[192:195] offset:26112
	ds_write_b64 v65, v[196:197] offset:34816
	v_add_f32_e32 v92, v198, v52
	v_mul_f32_e32 v92, 0x3fb8aa3b, v92
	v_exp_f32_e32 v92, v92
	v_mov_b32_e32 v52, v199
	ds_write_b32 v78, v92 offset:1024
	s_waitcnt lgkmcnt(14)
	s_cmp_eq_u32 s11, 0
	s_cbranch_scc1 .Lsc3_nopv1_0
	v_mfma_f32_16x16x32_bf16 v[172:175], v[132:135], v[168:171], v[172:175]

.Lsc3_noy_1:
	s_add_u32 s3, s34, 5
	s_min_u32 s3, s3, 67
	s_cmp_lt_u32 s3, 4
	s_cselect_b32 s4, s16, s17
	s_mul_i32 s5, s3, s15
	s_add_i32 s4, s4, s5
	s_lshl_b32 s5, s4, 16
	s_lshl_b32 s4, s4, 11
	s_add_u32 s40, s18, s5
	s_addc_u32 s41, s19, 0
	s_add_u32 s42, s20, s5
	s_addc_u32 s43, s21, 0
	s_add_u32 s44, s22, s5
	s_addc_u32 s45, s23, 0
	s_add_u32 s46, s24, s4
	s_addc_u32 s47, s25, 0
	s_add_u32 s50, s26, s4
	s_addc_u32 s51, s27, 0
	global_load_dwordx4 v[180:183], v53, s[40:41]
	global_load_dwordx4 v[184:187], v54, s[40:41]
	global_load_dwordx4 v[188:191], v53, s[42:43]
	global_load_dwordx4 v[192:195], v54, s[42:43]
	global_load_dwordx2 v[196:197], v55, s[44:45]
	global_load_dword v198, v56, s[46:47]
	global_load_dword v199, v56, s[50:51]
	s_waitcnt lgkmcnt(0)
	s_cmp_eq_u32 s13, 0
	s_cbranch_scc1 .Lsc3_nox2_1
	v_mfma_f32_16x16x32_bf16 v[152:155], v[112:115], v[96:99], 0
	v_mfma_f32_16x16x32_bf16 v[152:155], v[116:119], v[100:103], v[152:155]
	v_mfma_f32_16x16x32_bf16 v[152:155], v[120:123], v[104:107], v[152:155]
	v_mfma_f32_16x16x32_bf16 v[152:155], v[124:127], v[108:111], v[152:155]

.Lsc3_noy3_1:
	ds_write_b64 v85, v[160:161]
	ds_write_b64 v85, v[162:163] offset:1024
	s_waitcnt lgkmcnt(0)
	s_barrier
	ds_read_b64_tr_b16 v[112:113], v83 offset:0
	ds_read_b64_tr_b16 v[114:115], v83 offset:288
	ds_read_b64_tr_b16 v[116:117], v83 offset:2304
	ds_read_b64_tr_b16 v[118:119], v83 offset:2592
	ds_read_b64_tr_b16 v[120:121], v83 offset:4608
	ds_read_b64_tr_b16 v[122:123], v83 offset:4896
	ds_read_b64_tr_b16 v[124:125], v83 offset:6912
	ds_read_b64_tr_b16 v[126:127], v83 offset:7200
	ds_read_b64_tr_b16 v[128:129], v73 offset:34816
	ds_read_b64_tr_b16 v[130:131], v73 offset:35968
	ds_read_b64_tr_b16 v[132:133], v73 offset:37120
	ds_read_b64_tr_b16 v[134:135], v73 offset:38272
	ds_read_b128 v[164:167], v87
	ds_read_b128 v[168:171], v87 offset:1024
	s_waitcnt lgkmcnt(12)
	v_mfma_f32_16x16x32_bf16 v[172:175], v[112:115], v[96:99], 0
	ds_read_b64_tr_b16 v[136:137], v76 offset:17408
	ds_read_b64_tr_b16 v[138:139], v76 offset:21760
	s_waitcnt lgkmcnt(12)
	v_mfma_f32_16x16x32_bf16 v[172:175], v[116:119], v[100:103], v[172:175]
	ds_read_b64_tr_b16 v[140:141], v76 offset:17440
	ds_read_b64_tr_b16 v[142:143], v76 offset:21792
	s_waitcnt lgkmcnt(12)
	v_mfma_f32_16x16x32_bf16 v[172:175], v[120:123], v[104:107], v[172:175]
	ds_read_b64_tr_b16 v[144:145], v76 offset:26112
	ds_read_b64_tr_b16 v[146:147], v76 offset:30464
	s_waitcnt lgkmcnt(12)
	v_mfma_f32_16x16x32_bf16 v[172:175], v[124:127], v[108:111], v[172:175]
	ds_read_b64_tr_b16 v[148:149], v76 offset:26144
	ds_read_b64_tr_b16 v[150:151], v76 offset:30496
	s_waitcnt lgkmcnt(9)
	v_mfma_f32_16x16x32_bf16 v[172:175], v[128:131], v[164:167], v[172:175]
	s_waitcnt vmcnt(16)
	ds_write_b128 v60, v[2:5] offset:0
	ds_write_b128 v60, v[6:9] offset:8704
	ds_write_b128 v60, v[10:13] offset:17408
	ds_write_b128 v60, v[14:17] offset:26112
	ds_write_b64 v63, v[18:19] offset:34816
	v_add_f32_e32 v92, v20, v52
	v_mul_f32_e32 v92, 0x3fb8aa3b, v92
	v_exp_f32_e32 v92, v92
	v_mov_b32_e32 v52, v21
	ds_write_b32 v78, v92 offset:0
	s_waitcnt lgkmcnt(14)
	s_cmp_eq_u32 s11, 0
	s_cbranch_scc1 .Lsc3_nopv1_1
	v_mfma_f32_16x16x32_bf16 v[172:175], v[132:135], v[168:171], v[172:175]

.Lsc3_nox_2:
	s_cmp_eq_u32 s14, 0
	s_cbranch_scc1 .Lsc3_noy_2
	ds_read_b128 v[128:131], v71 offset:26112
	ds_read_b128 v[132:135], v71 offset:26176
	ds_read_b128 v[136:139], v71 offset:26240
	ds_read_b128 v[140:143], v71 offset:26304
.Lsc3_noy_2:
	s_add_u32 s3, s34, 6
	s_min_u32 s3, s3, 67
	s_cmp_lt_u32 s3, 4
	s_cselect_b32 s4, s16, s17
	s_mul_i32 s5, s3, s15
	s_add_i32 s4, s4, s5
	s_lshl_b32 s5, s4, 16
	s_lshl_b32 s4, s4, 11
	s_add_u32 s40, s18, s5
	s_addc_u32 s41, s19, 0
	s_add_u32 s42, s20, s5
	s_addc_u32 s43, s21, 0
	s_add_u32 s44, s22, s5
	s_addc_u32 s45, s23, 0
	s_add_u32 s46, s24, s4
	s_addc_u32 s47, s25, 0
	s_add_u32 s50, s26, s4
	s_addc_u32 s51, s27, 0
	global_load_dwordx4 v[2:5], v53, s[40:41]
	global_load_dwordx4 v[6:9], v54, s[40:41]
	global_load_dwordx4 v[10:13], v53, s[42:43]
	global_load_dwordx4 v[14:17], v54, s[42:43]
	global_load_dwordx2 v[18:19], v55, s[44:45]
	global_load_dword v20, v56, s[46:47]
	global_load_dword v21, v56, s[50:51]
	s_waitcnt lgkmcnt(0)
	s_cmp_eq_u32 s13, 0
	s_cbranch_scc1 .Lsc3_nox2_2
	v_mfma_f32_16x16x32_bf16 v[152:155], v[112:115], v[96:99], 0
	v_mfma_f32_16x16x32_bf16 v[152:155], v[116:119], v[100:103], v[152:155]
	v_mfma_f32_16x16x32_bf16 v[152:155], v[120:123], v[104:107], v[152:155]
	v_mfma_f32_16x16x32_bf16 v[152:155], v[124:127], v[108:111], v[152:155]

.Lsc3_noy3_2:
	ds_write_b64 v84, v[160:161]
	ds_write_b64 v84, v[162:163] offset:1024
	s_waitcnt lgkmcnt(0)
	s_barrier
	ds_read_b64_tr_b16 v[112:113], v82 offset:0
	ds_read_b64_tr_b16 v[114:115], v82 offset:288
	ds_read_b64_tr_b16 v[116:117], v82 offset:2304
	ds_read_b64_tr_b16 v[118:119], v82 offset:2592
	ds_read_b64_tr_b16 v[120:121], v82 offset:4608
	ds_read_b64_tr_b16 v[122:123], v82 offset:4896
	ds_read_b64_tr_b16 v[124:125], v82 offset:6912
	ds_read_b64_tr_b16 v[126:127], v82 offset:7200
	ds_read_b64_tr_b16 v[128:129], v74 offset:34816
	ds_read_b64_tr_b16 v[130:131], v74 offset:35968
	ds_read_b64_tr_b16 v[132:133], v74 offset:37120
	ds_read_b64_tr_b16 v[134:135], v74 offset:38272
	ds_read_b128 v[164:167], v86
	ds_read_b128 v[168:171], v86 offset:1024
	s_waitcnt lgkmcnt(12)
	v_mfma_f32_16x16x32_bf16 v[172:175], v[112:115], v[96:99], 0
	ds_read_b64_tr_b16 v[136:137], v77 offset:17408
	ds_read_b64_tr_b16 v[138:139], v77 offset:21760
	s_waitcnt lgkmcnt(12)
	v_mfma_f32_16x16x32_bf16 v[172:175], v[116:119], v[100:103], v[172:175]
	ds_read_b64_tr_b16 v[140:141], v77 offset:17440
	ds_read_b64_tr_b16 v[142:143], v77 offset:21792
	s_waitcnt lgkmcnt(12)
	v_mfma_f32_16x16x32_bf16 v[172:175], v[120:123], v[104:107], v[172:175]
	ds_read_b64_tr_b16 v[144:145], v77 offset:26112
	ds_read_b64_tr_b16 v[146:147], v77 offset:30464
	s_waitcnt lgkmcnt(12)
	v_mfma_f32_16x16x32_bf16 v[172:175], v[124:127], v[108:111], v[172:175]
	ds_read_b64_tr_b16 v[148:149], v77 offset:26144
	ds_read_b64_tr_b16 v[150:151], v77 offset:30496
	s_waitcnt lgkmcnt(9)
	v_mfma_f32_16x16x32_bf16 v[172:175], v[128:131], v[164:167], v[172:175]
	s_waitcnt vmcnt(16)
	ds_write_b128 v61, v[22:25] offset:0
	ds_write_b128 v61, v[26:29] offset:8704
	ds_write_b128 v61, v[30:33] offset:17408
	ds_write_b128 v61, v[34:37] offset:26112
	ds_write_b64 v64, v[38:39] offset:34816
	v_add_f32_e32 v92, v40, v52
	v_mul_f32_e32 v92, 0x3fb8aa3b, v92
	v_exp_f32_e32 v92, v92
	v_mov_b32_e32 v52, v41
	ds_write_b32 v78, v92 offset:512
	s_waitcnt lgkmcnt(14)
	s_cmp_eq_u32 s11, 0
	s_cbranch_scc1 .Lsc3_nopv1_2
	v_mfma_f32_16x16x32_bf16 v[172:175], v[132:135], v[168:171], v[172:175]

.Lsc3_nox_3:
	s_cmp_eq_u32 s14, 0
	s_cbranch_scc1 .Lsc3_noy_3
	ds_read_b128 v[128:131], v69 offset:26112
	ds_read_b128 v[132:135], v69 offset:26176
	ds_read_b128 v[136:139], v69 offset:26240
	ds_read_b128 v[140:143], v69 offset:26304
.Lsc3_noy_3:
	s_add_u32 s3, s34, 7
	s_min_u32 s3, s3, 67
	s_cmp_lt_u32 s3, 4
	s_cselect_b32 s4, s16, s17
	s_mul_i32 s5, s3, s15
	s_add_i32 s4, s4, s5
	s_lshl_b32 s5, s4, 16
	s_lshl_b32 s4, s4, 11
	s_add_u32 s40, s18, s5
	s_addc_u32 s41, s19, 0
	s_add_u32 s42, s20, s5
	s_addc_u32 s43, s21, 0
	s_add_u32 s44, s22, s5
	s_addc_u32 s45, s23, 0
	s_add_u32 s46, s24, s4
	s_addc_u32 s47, s25, 0
	s_add_u32 s50, s26, s4
	s_addc_u32 s51, s27, 0
	global_load_dwordx4 v[22:25], v53, s[40:41]
	global_load_dwordx4 v[26:29], v54, s[40:41]
	global_load_dwordx4 v[30:33], v53, s[42:43]
	global_load_dwordx4 v[34:37], v54, s[42:43]
	global_load_dwordx2 v[38:39], v55, s[44:45]
	global_load_dword v40, v56, s[46:47]
	global_load_dword v41, v56, s[50:51]
	s_waitcnt lgkmcnt(0)
	s_cmp_eq_u32 s13, 0
	s_cbranch_scc1 .Lsc3_nox2_3
	v_mfma_f32_16x16x32_bf16 v[152:155], v[112:115], v[96:99], 0
	v_mfma_f32_16x16x32_bf16 v[152:155], v[116:119], v[100:103], v[152:155]
	v_mfma_f32_16x16x32_bf16 v[152:155], v[120:123], v[104:107], v[152:155]
	v_mfma_f32_16x16x32_bf16 v[152:155], v[124:127], v[108:111], v[152:155]

.Lsc3_noy3_3:
	ds_write_b64 v85, v[160:161]
	ds_write_b64 v85, v[162:163] offset:1024
	s_waitcnt lgkmcnt(0)
	s_barrier
	ds_read_b64_tr_b16 v[112:113], v83 offset:0
	ds_read_b64_tr_b16 v[114:115], v83 offset:288
	ds_read_b64_tr_b16 v[116:117], v83 offset:2304
	ds_read_b64_tr_b16 v[118:119], v83 offset:2592
	ds_read_b64_tr_b16 v[120:121], v83 offset:4608
	ds_read_b64_tr_b16 v[122:123], v83 offset:4896
	ds_read_b64_tr_b16 v[124:125], v83 offset:6912
	ds_read_b64_tr_b16 v[126:127], v83 offset:7200
	ds_read_b64_tr_b16 v[128:129], v72 offset:34816
	ds_read_b64_tr_b16 v[130:131], v72 offset:35968
	ds_read_b64_tr_b16 v[132:133], v72 offset:37120
	ds_read_b64_tr_b16 v[134:135], v72 offset:38272
	ds_read_b128 v[164:167], v87
	ds_read_b128 v[168:171], v87 offset:1024
	s_waitcnt lgkmcnt(12)
	v_mfma_f32_16x16x32_bf16 v[172:175], v[112:115], v[96:99], 0
	ds_read_b64_tr_b16 v[136:137], v75 offset:17408
	ds_read_b64_tr_b16 v[138:139], v75 offset:21760
	s_waitcnt lgkmcnt(12)
	v_mfma_f32_16x16x32_bf16 v[172:175], v[116:119], v[100:103], v[172:175]
	ds_read_b64_tr_b16 v[140:141], v75 offset:17440
	ds_read_b64_tr_b16 v[142:143], v75 offset:21792
	s_waitcnt lgkmcnt(12)
	v_mfma_f32_16x16x32_bf16 v[172:175], v[120:123], v[104:107], v[172:175]
	ds_read_b64_tr_b16 v[144:145], v75 offset:26112
	ds_read_b64_tr_b16 v[146:147], v75 offset:30464
	s_waitcnt lgkmcnt(12)
	v_mfma_f32_16x16x32_bf16 v[172:175], v[124:127], v[108:111], v[172:175]
	ds_read_b64_tr_b16 v[148:149], v75 offset:26144
	ds_read_b64_tr_b16 v[150:151], v75 offset:30496
	s_waitcnt lgkmcnt(9)
	v_mfma_f32_16x16x32_bf16 v[172:175], v[128:131], v[164:167], v[172:175]
	s_waitcnt vmcnt(16)
	ds_write_b128 v62, v[180:183] offset:0
	ds_write_b128 v62, v[184:187] offset:8704
	ds_write_b128 v62, v[188:191] offset:17408
	ds_write_b128 v62, v[192:195] offset:26112
	ds_write_b64 v65, v[196:197] offset:34816
	v_add_f32_e32 v92, v198, v52
	v_mul_f32_e32 v92, 0x3fb8aa3b, v92
	v_exp_f32_e32 v92, v92
	v_mov_b32_e32 v52, v199
	ds_write_b32 v78, v92 offset:1024
	s_waitcnt lgkmcnt(14)
	s_cmp_eq_u32 s11, 0
	s_cbranch_scc1 .Lsc3_nopv1_3
	v_mfma_f32_16x16x32_bf16 v[172:175], v[132:135], v[168:171], v[172:175]

.Lsc3_noy_4:
	s_add_u32 s3, s34, 8
	s_min_u32 s3, s3, 67
	s_cmp_lt_u32 s3, 4
	s_cselect_b32 s4, s16, s17
	s_mul_i32 s5, s3, s15
	s_add_i32 s4, s4, s5
	s_lshl_b32 s5, s4, 16
	s_lshl_b32 s4, s4, 11
	s_add_u32 s40, s18, s5
	s_addc_u32 s41, s19, 0
	s_add_u32 s42, s20, s5
	s_addc_u32 s43, s21, 0
	s_add_u32 s44, s22, s5
	s_addc_u32 s45, s23, 0
	s_add_u32 s46, s24, s4
	s_addc_u32 s47, s25, 0
	s_add_u32 s50, s26, s4
	s_addc_u32 s51, s27, 0
	global_load_dwordx4 v[180:183], v53, s[40:41]
	global_load_dwordx4 v[184:187], v54, s[40:41]
	global_load_dwordx4 v[188:191], v53, s[42:43]
	global_load_dwordx4 v[192:195], v54, s[42:43]
	global_load_dwordx2 v[196:197], v55, s[44:45]
	global_load_dword v198, v56, s[46:47]
	global_load_dword v199, v56, s[50:51]
	s_waitcnt lgkmcnt(0)
	s_cmp_eq_u32 s13, 0
	s_cbranch_scc1 .Lsc3_nox2_4
	v_mfma_f32_16x16x32_bf16 v[152:155], v[112:115], v[96:99], 0
	v_mfma_f32_16x16x32_bf16 v[152:155], v[116:119], v[100:103], v[152:155]
	v_mfma_f32_16x16x32_bf16 v[152:155], v[120:123], v[104:107], v[152:155]
	v_mfma_f32_16x16x32_bf16 v[152:155], v[124:127], v[108:111], v[152:155]

.Lsc3_noy3_4:
	ds_write_b64 v84, v[160:161]
	ds_write_b64 v84, v[162:163] offset:1024
	s_waitcnt lgkmcnt(0)
	s_barrier
	ds_read_b64_tr_b16 v[112:113], v82 offset:0
	ds_read_b64_tr_b16 v[114:115], v82 offset:288
	ds_read_b64_tr_b16 v[116:117], v82 offset:2304
	ds_read_b64_tr_b16 v[118:119], v82 offset:2592
	ds_read_b64_tr_b16 v[120:121], v82 offset:4608
	ds_read_b64_tr_b16 v[122:123], v82 offset:4896
	ds_read_b64_tr_b16 v[124:125], v82 offset:6912
	ds_read_b64_tr_b16 v[126:127], v82 offset:7200
	ds_read_b64_tr_b16 v[128:129], v73 offset:34816
	ds_read_b64_tr_b16 v[130:131], v73 offset:35968
	ds_read_b64_tr_b16 v[132:133], v73 offset:37120
	ds_read_b64_tr_b16 v[134:135], v73 offset:38272
	ds_read_b128 v[164:167], v86
	ds_read_b128 v[168:171], v86 offset:1024
	s_waitcnt lgkmcnt(12)
	v_mfma_f32_16x16x32_bf16 v[172:175], v[112:115], v[96:99], 0
	ds_read_b64_tr_b16 v[136:137], v76 offset:17408
	ds_read_b64_tr_b16 v[138:139], v76 offset:21760
	s_waitcnt lgkmcnt(12)
	v_mfma_f32_16x16x32_bf16 v[172:175], v[116:119], v[100:103], v[172:175]
	ds_read_b64_tr_b16 v[140:141], v76 offset:17440
	ds_read_b64_tr_b16 v[142:143], v76 offset:21792
	s_waitcnt lgkmcnt(12)
	v_mfma_f32_16x16x32_bf16 v[172:175], v[120:123], v[104:107], v[172:175]
	ds_read_b64_tr_b16 v[144:145], v76 offset:26112
	ds_read_b64_tr_b16 v[146:147], v76 offset:30464
	s_waitcnt lgkmcnt(12)
	v_mfma_f32_16x16x32_bf16 v[172:175], v[124:127], v[108:111], v[172:175]
	ds_read_b64_tr_b16 v[148:149], v76 offset:26144
	ds_read_b64_tr_b16 v[150:151], v76 offset:30496
	s_waitcnt lgkmcnt(9)
	v_mfma_f32_16x16x32_bf16 v[172:175], v[128:131], v[164:167], v[172:175]
	s_waitcnt vmcnt(16)
	ds_write_b128 v60, v[2:5] offset:0
	ds_write_b128 v60, v[6:9] offset:8704
	ds_write_b128 v60, v[10:13] offset:17408
	ds_write_b128 v60, v[14:17] offset:26112
	ds_write_b64 v63, v[18:19] offset:34816
	v_add_f32_e32 v92, v20, v52
	v_mul_f32_e32 v92, 0x3fb8aa3b, v92
	v_exp_f32_e32 v92, v92
	v_mov_b32_e32 v52, v21
	ds_write_b32 v78, v92 offset:0
	s_waitcnt lgkmcnt(14)
	s_cmp_eq_u32 s11, 0
	s_cbranch_scc1 .Lsc3_nopv1_4
	v_mfma_f32_16x16x32_bf16 v[172:175], v[132:135], v[168:171], v[172:175]

.Lsc3_noy_5:
	s_add_u32 s3, s34, 9
	s_min_u32 s3, s3, 67
	s_cmp_lt_u32 s3, 4
	s_cselect_b32 s4, s16, s17
	s_mul_i32 s5, s3, s15
	s_add_i32 s4, s4, s5
	s_lshl_b32 s5, s4, 16
	s_lshl_b32 s4, s4, 11
	s_add_u32 s40, s18, s5
	s_addc_u32 s41, s19, 0
	s_add_u32 s42, s20, s5
	s_addc_u32 s43, s21, 0
	s_add_u32 s44, s22, s5
	s_addc_u32 s45, s23, 0
	s_add_u32 s46, s24, s4
	s_addc_u32 s47, s25, 0
	s_add_u32 s50, s26, s4
	s_addc_u32 s51, s27, 0
	global_load_dwordx4 v[2:5], v53, s[40:41]
	global_load_dwordx4 v[6:9], v54, s[40:41]
	global_load_dwordx4 v[10:13], v53, s[42:43]
	global_load_dwordx4 v[14:17], v54, s[42:43]
	global_load_dwordx2 v[18:19], v55, s[44:45]
	global_load_dword v20, v56, s[46:47]
	global_load_dword v21, v56, s[50:51]
	s_waitcnt lgkmcnt(0)
	s_cmp_eq_u32 s13, 0
	s_cbranch_scc1 .Lsc3_nox2_5
	v_mfma_f32_16x16x32_bf16 v[152:155], v[112:115], v[96:99], 0
	v_mfma_f32_16x16x32_bf16 v[152:155], v[116:119], v[100:103], v[152:155]
	v_mfma_f32_16x16x32_bf16 v[152:155], v[120:123], v[104:107], v[152:155]
	v_mfma_f32_16x16x32_bf16 v[152:155], v[124:127], v[108:111], v[152:155]

.Lsc3_noy3_5:
	ds_write_b64 v85, v[160:161]
	ds_write_b64 v85, v[162:163] offset:1024
	s_waitcnt lgkmcnt(0)
	s_barrier
	ds_read_b64_tr_b16 v[112:113], v83 offset:0
	ds_read_b64_tr_b16 v[114:115], v83 offset:288
	ds_read_b64_tr_b16 v[116:117], v83 offset:2304
	ds_read_b64_tr_b16 v[118:119], v83 offset:2592
	ds_read_b64_tr_b16 v[120:121], v83 offset:4608
	ds_read_b64_tr_b16 v[122:123], v83 offset:4896
	ds_read_b64_tr_b16 v[124:125], v83 offset:6912
	ds_read_b64_tr_b16 v[126:127], v83 offset:7200
	ds_read_b64_tr_b16 v[128:129], v74 offset:34816
	ds_read_b64_tr_b16 v[130:131], v74 offset:35968
	ds_read_b64_tr_b16 v[132:133], v74 offset:37120
	ds_read_b64_tr_b16 v[134:135], v74 offset:38272
	ds_read_b128 v[164:167], v87
	ds_read_b128 v[168:171], v87 offset:1024
	s_waitcnt lgkmcnt(12)
	v_mfma_f32_16x16x32_bf16 v[172:175], v[112:115], v[96:99], 0
	ds_read_b64_tr_b16 v[136:137], v77 offset:17408
	ds_read_b64_tr_b16 v[138:139], v77 offset:21760
	s_waitcnt lgkmcnt(12)
	v_mfma_f32_16x16x32_bf16 v[172:175], v[116:119], v[100:103], v[172:175]
	ds_read_b64_tr_b16 v[140:141], v77 offset:17440
	ds_read_b64_tr_b16 v[142:143], v77 offset:21792
	s_waitcnt lgkmcnt(12)
	v_mfma_f32_16x16x32_bf16 v[172:175], v[120:123], v[104:107], v[172:175]
	ds_read_b64_tr_b16 v[144:145], v77 offset:26112
	ds_read_b64_tr_b16 v[146:147], v77 offset:30464
	s_waitcnt lgkmcnt(12)
	v_mfma_f32_16x16x32_bf16 v[172:175], v[124:127], v[108:111], v[172:175]
	ds_read_b64_tr_b16 v[148:149], v77 offset:26144
	ds_read_b64_tr_b16 v[150:151], v77 offset:30496
	s_waitcnt lgkmcnt(9)
	v_mfma_f32_16x16x32_bf16 v[172:175], v[128:131], v[164:167], v[172:175]
	s_waitcnt vmcnt(16)
	ds_write_b128 v61, v[22:25] offset:0
	ds_write_b128 v61, v[26:29] offset:8704
	ds_write_b128 v61, v[30:33] offset:17408
	ds_write_b128 v61, v[34:37] offset:26112
	ds_write_b64 v64, v[38:39] offset:34816
	v_add_f32_e32 v92, v40, v52
	v_mul_f32_e32 v92, 0x3fb8aa3b, v92
	v_exp_f32_e32 v92, v92
	v_mov_b32_e32 v52, v41
	ds_write_b32 v78, v92 offset:512
	s_waitcnt lgkmcnt(14)
	s_cmp_eq_u32 s11, 0
	s_cbranch_scc1 .Lsc3_nopv1_5
	v_mfma_f32_16x16x32_bf16 v[172:175], v[132:135], v[168:171], v[172:175]
